# attention units: third V buffer with rotating bases, barrier between PV and LDS staging writes removed (one barrier per key tile)
# baseline (speedup 1.0000x reference)
.LBB0_1083:
	s_lshl_b32 s6, s9, 8
	s_addk_i32 s6, 0x100
	s_cmpk_gt_u32 s8, 0x23f
	s_mul_i32 s8, s33, 0x900
	s_movk_i32 s9, 0x900
	s_cselect_b32 s6, 0, s6
	s_mul_hi_u32 s7, s33, 0x900
	s_cselect_b32 s72, 0x100, s9
	s_add_u32 s26, s8, s6
	s_addc_u32 s27, s7, 0
	s_andn2_b64 vcc, exec, s[4:5]
	v_and_b32_e32 v165, 63, v168
	v_bfe_u32 v183, v168, 5, 1
	v_ashrrev_i32_e32 v0, 1, v168
	v_lshlrev_b32_e32 v1, 3, v168
	v_lshlrev_b32_e32 v2, 1, v168
	s_movk_i32 s4, 0xffe0
	s_mov_b64 s[8:9], -1
	v_and_b32_e32 v184, 31, v168
	v_and_b32_e32 v166, 0x3fffffc0, v168
	v_and_b32_e32 v164, 15, v168
	s_mul_hi_u32 s92, s33, 0x1200000
	s_mul_i32 s94, s33, 0x1200000
	v_and_b32_e32 v185, 0xffffffe0, v0
	v_bfi_b32 v154, s4, v0, v168
	v_lshlrev_b32_e32 v178, 4, v183
	v_ashrrev_i32_e32 v152, 4, v168
	v_and_b32_e32 v172, 0x78, v1
	v_bfe_u32 v171, v1, 5, 2
	v_lshlrev_b32_e32 v170, 4, v168
	v_lshlrev_b32_e32 v169, 3, v165
	v_and_b32_e32 v167, 32, v2
	v_cmp_gt_u32_e64 s[6:7], 32, v165
	s_mul_i32 s25, s27, 0xc00
	s_mul_hi_u32 s37, s26, 0xc00
	s_mul_i32 s51, s26, 0xc00
	s_cbranch_vccz .LBB0_1104
	s_lshl_b64 s[4:5], s[26:27], 13
	v_readlane_b32 s8, v253, 56
	v_readlane_b32 s9, v253, 57
	s_add_u32 s4, s8, s4
	s_addc_u32 s5, s9, s5
	s_lshl_b32 s90, s73, 7
	s_lshl_b32 s30, s73, 8
	s_add_u32 s4, s4, s30
	s_addc_u32 s5, s5, 0
	s_lshl_b32 s10, s28, 7
	s_add_u32 s4, s4, s10
	s_addc_u32 s5, s5, 0
	s_add_u32 s8, s8, s94
	s_addc_u32 s9, s9, s92
	s_add_u32 s8, s8, s30
	v_ashrrev_i32_e32 v153, 31, v152
	s_addc_u32 s9, s9, 0
	v_add_u32_e32 v12, 32, v152
	v_lshlrev_b64 v[48:49], 13, v[152:153]
	v_lshl_add_u64 v[0:1], s[8:9], 0, v[48:49]
	v_lshlrev_b32_e32 v176, 1, v172
	v_ashrrev_i32_e32 v13, 31, v12
	v_ashrrev_i32_e32 v14, 3, v168
	v_lshl_add_u64 v[52:53], v[0:1], 0, v[176:177]
	v_lshlrev_b64 v[0:1], 13, v[12:13]
	s_add_u32 s10, s8, s10
	v_lshl_add_u64 v[0:1], s[8:9], 0, v[0:1]
	v_ashrrev_i32_e32 v15, 31, v14
	s_addc_u32 s11, s9, 0
	v_lshl_add_u64 v[4:5], v[0:1], 0, v[176:177]
	v_lshlrev_b64 v[50:51], 13, v[14:15]
	global_load_dwordx4 v[0:3], v[52:53], off offset:3072
	s_nop 0
	global_load_dwordx4 v[4:7], v[4:5], off offset:3072
	v_lshl_add_u64 v[8:9], s[10:11], 0, v[50:51]
	v_and_b32_e32 v176, 0x70, v170
	v_lshl_add_u64 v[54:55], v[8:9], 0, v[176:177]
	global_load_dwordx4 v[8:11], v[54:55], off offset:1536
	v_ashrrev_i32_e32 v155, 31, v154
	v_lshlrev_b64 v[16:17], 13, v[154:155]
	v_lshl_add_u64 v[16:17], s[4:5], 0, v[16:17]
	v_mov_b32_e32 v179, v177
	v_lshl_add_u64 v[16:17], v[16:17], 0, v[178:179]
	global_load_dwordx4 v[108:111], v[16:17], off
	global_load_dwordx4 v[100:103], v[16:17], off offset:32
	global_load_dwordx4 v[96:99], v[16:17], off offset:64
	global_load_dwordx4 v[104:107], v[16:17], off offset:96
	v_and_b32_e32 v13, 0xfffff0, v152
	v_lshlrev_b32_e32 v15, 1, v152
	v_lshrrev_b32_e32 v18, 1, v152
	v_and_b32_e32 v19, 3, v152
	v_and_or_b32 v13, v15, 8, v13
	v_and_or_b32 v15, v18, 4, v19
	v_and_b32_e32 v18, 0xfffff0, v12
	v_lshlrev_b32_e32 v12, 1, v12
	v_lshrrev_b32_e32 v13, 1, v13
	v_and_or_b32 v12, v12, 8, v18
	v_or_b32_e32 v13, v13, v171
	v_lshrrev_b32_e32 v12, 1, v12
	v_and_b32_e32 v20, 48, v170
	v_lshlrev_b32_e32 v15, 6, v15
	v_lshlrev_b32_e32 v13, 9, v13
	v_or_b32_e32 v12, v12, v171
	v_lshlrev_b32_e32 v68, 7, v184
	v_lshlrev_b32_e32 v19, 7, v14
	v_lshlrev_b32_e32 v14, 4, v14
	v_or3_b32 v13, v13, v15, v20
	v_lshlrev_b32_e32 v12, 9, v12
	v_and_b32_e32 v14, 0x70, v14
	v_or3_b32 v12, v12, v15, v20
	v_add_u32_e32 v179, 0, v13
	v_bitop3_b32 v13, v178, v68, v176 bitop3:0xde
	v_add_u32_e32 v180, 0, v12
	v_bitop3_b32 v12, v14, v19, v176 bitop3:0xde
	v_add_u32_e32 v181, 0, v13
	v_add_u32_e32 v186, 0, v12
	s_waitcnt vmcnt(0)
	s_mov_b32 s5, 0x80000
	s_mov_b32 s4, 0xc0000
	v_and_b32_e32 v12, 0x100, v169
	s_mov_b32 s8, s91
	s_mov_b32 s9, s91
	s_mov_b32 s10, s91
	s_mov_b32 s11, s91
	s_mov_b32 s12, s91
	s_mov_b32 s13, s91
	s_mov_b32 s14, s91
	s_mov_b32 s15, s91
	s_mov_b32 s16, s91
	s_mov_b32 s17, s91
	s_mov_b32 s18, s91
	s_mov_b32 s19, s91
	s_mov_b32 s20, s91
	s_mov_b32 s21, s91
	s_mov_b32 s22, s91
	s_mov_b32 s23, s91
	s_cmp_lg_u32 0, -1
	s_mov_b32 s29, s91
	s_waitcnt vmcnt(0)
	ds_write_b128 v179, v[0:3]
	ds_write_b128 v180, v[4:7]
	ds_write_b128 v186, v[8:11] offset:32768
	s_waitcnt lgkmcnt(0)
	s_barrier
	ds_read_b128 v[0:3], v181 offset:32768
	ds_read_b128 v[4:7], v181 offset:36864
	s_waitcnt lgkmcnt(1)
	v_mfma_f32_32x32x16_bf16 v[16:31], v[0:3], v[108:111], 0
	v_or_b32_e32 v0, 32, v178
	v_bitop3_b32 v0, v0, v68, v176 bitop3:0xde
	v_or_b32_e32 v1, 64, v178
	v_add_u32_e32 v187, 0, v0
	v_bitop3_b32 v14, v1, v68, v176 bitop3:0xde
	ds_read_b128 v[0:3], v187 offset:32768
	v_and_b32_e32 v8, 0xc0, v170
	v_and_or_b32 v13, v169, 24, v8
	v_add_co_u32_e32 v8, vcc, s5, v52
	s_waitcnt lgkmcnt(1)
	v_mfma_f32_32x32x16_bf16 v[32:47], v[4:7], v[108:111], 0
	v_addc_co_u32_e32 v9, vcc, 0, v53, vcc
	v_add_co_u32_e32 v10, vcc, s4, v52
	ds_read_b128 v[4:7], v187 offset:36864
	s_nop 0
	v_addc_co_u32_e32 v11, vcc, 0, v53, vcc
	s_waitcnt lgkmcnt(1)
	v_mfma_f32_32x32x16_bf16 v[16:31], v[0:3], v[100:103], v[16:31]
	v_add_co_u32_e32 v0, vcc, s5, v54
	v_add_u32_e32 v188, 0, v14
	s_nop 0
	v_addc_co_u32_e32 v1, vcc, 0, v55, vcc
	global_load_dwordx4 v[56:59], v[8:9], off offset:3072
	global_load_dwordx4 v[60:63], v[10:11], off offset:3072
	global_load_dwordx4 v[64:67], v[0:1], off offset:1536
	ds_read_b128 v[0:3], v188 offset:32768
	s_waitcnt lgkmcnt(1)
	v_mfma_f32_32x32x16_bf16 v[32:47], v[4:7], v[100:103], v[32:47]
	ds_read_b128 v[4:7], v188 offset:36864
	s_mov_b32 s5, 0x100000
	v_or3_b32 v72, v13, v167, v12
	v_add_co_u32_e32 v54, vcc, s5, v54
	s_cselect_b32 s4, 0, 0
	s_nop 0
	v_addc_co_u32_e32 v55, vcc, 0, v55, vcc
	s_waitcnt lgkmcnt(1)
	v_mfma_f32_32x32x16_bf16 v[16:31], v[0:3], v[96:99], v[16:31]
	v_or_b32_e32 v0, 0x60, v178
	v_bitop3_b32 v0, v0, v68, v176 bitop3:0xde
	v_add_u32_e32 v176, 0, v0
	ds_read_b128 v[0:3], v176 offset:32768
	ds_read_b128 v[68:71], v176 offset:36864
	global_load_dwordx4 v[120:123], v[54:55], off offset:1536
	s_lshr_b32 s47, s72, 6
	s_waitcnt lgkmcnt(2)
	v_mfma_f32_32x32x16_bf16 v[32:47], v[4:7], v[96:99], v[32:47]
	v_add_u32_e32 v175, s4, v72
	v_lshl_add_u32 v153, v166, 2, 0
	s_mov_b32 s31, s91
	s_mov_b32 s46, 4
	v_lshl_add_u32 v155, v184, 2, v153
	v_mov_b32_e32 v173, 0
	s_waitcnt lgkmcnt(1)
	v_mfma_f32_32x32x16_bf16 v[16:31], v[0:3], v[104:107], v[16:31]
	v_mov_b64_e32 v[0:1], s[8:9]
	v_mov_b64_e32 v[2:3], s[10:11]
	v_mov_b64_e32 v[4:5], s[12:13]
	v_mov_b64_e32 v[6:7], s[14:15]
	v_mov_b64_e32 v[8:9], s[16:17]
	v_mov_b64_e32 v[10:11], s[18:19]
	v_mov_b64_e32 v[12:13], s[20:21]
	v_mov_b64_e32 v[14:15], s[22:23]
	s_mov_b32 s8, 0x140000
	v_add_co_u32_e32 v54, vcc, s8, v52
	s_waitcnt lgkmcnt(0)
	v_mfma_f32_32x32x16_bf16 v[32:47], v[68:71], v[104:107], v[32:47]
	v_addc_co_u32_e32 v55, vcc, 0, v53, vcc
	v_add_co_u32_e32 v52, vcc, s5, v52
	v_max_f32_e32 v68, v17, v17
	s_nop 0
	v_addc_co_u32_e32 v53, vcc, 0, v53, vcc
	global_load_dwordx4 v[116:119], v[54:55], off offset:3072
	global_load_dwordx4 v[112:115], v[52:53], off offset:3072
	v_max_f32_e32 v69, v16, v16
	v_max_f32_e32 v68, v69, v68
	v_max3_f32 v68, v68, v18, v19
	v_max3_f32 v68, v68, v20, v21
	v_max3_f32 v68, v68, v22, v23
	v_max3_f32 v68, v68, v24, v25
	v_max3_f32 v68, v68, v26, v27
	v_max3_f32 v68, v68, v28, v29
	v_max3_f32 v68, v68, v30, v31
	v_max3_f32 v68, v68, v32, v33
	v_max3_f32 v68, v68, v34, v35
	v_max3_f32 v68, v68, v36, v37
	v_max3_f32 v68, v68, v38, v39
	v_max3_f32 v68, v68, v40, v41
	v_max3_f32 v68, v68, v42, v43
	v_max3_f32 v68, v68, v44, v45
	v_max3_f32 v68, v68, v46, v47
	v_mov_b32_e32 v69, v68
	s_nop 1
	v_permlane32_swap_b32_e32 v68, v69
	v_max_f32_e32 v69, v69, v69
	v_max_f32_e32 v52, v68, v68
	v_max_f32_e32 v52, v52, v69
	v_add_f32_e32 v53, 0x7149f2ca, v52
	v_cmp_ge_f32_e32 vcc, s38, v53
	s_cmp_eq_u64 vcc, exec
	v_max_f32_e32 v52, 0xf149f2ca, v52
	s_cselect_b64 vcc, -1, 0
	v_cndmask_b32_e32 v140, v52, v227, vcc
	v_sub_f32_e32 v53, 0xf149f2ca, v52
	v_mul_f32_e32 v52, 0xbe38aa3b, v140
	v_fmamk_f32 v16, v16, 0x3e38aa3b, v52
	v_exp_f32_e32 v144, v16
	v_fmamk_f32 v16, v17, 0x3e38aa3b, v52
	v_exp_f32_e32 v146, v16
	v_fmamk_f32 v16, v18, 0x3e38aa3b, v52
	v_exp_f32_e32 v148, v16
	v_fmamk_f32 v16, v19, 0x3e38aa3b, v52
	v_exp_f32_e32 v150, v16
	v_fmamk_f32 v16, v20, 0x3e38aa3b, v52
	v_exp_f32_e32 v160, v16
	v_fmamk_f32 v16, v21, 0x3e38aa3b, v52
	v_exp_f32_e32 v162, v16
	v_fmamk_f32 v16, v22, 0x3e38aa3b, v52
	v_exp_f32_e32 v163, v16
	v_fmamk_f32 v16, v23, 0x3e38aa3b, v52
	v_exp_f32_e32 v196, v16
	v_fmamk_f32 v16, v24, 0x3e38aa3b, v52
	v_exp_f32_e32 v142, v16
	v_fmamk_f32 v16, v25, 0x3e38aa3b, v52
	v_exp_f32_e32 v143, v16
	v_fmamk_f32 v16, v26, 0x3e38aa3b, v52
	v_mul_f32_e32 v53, 0x3e38aa3b, v53
	v_exp_f32_e32 v145, v16
	v_fmamk_f32 v16, v27, 0x3e38aa3b, v52
	s_addk_i32 s4, 0x4000
	v_exp_f32_e32 v53, v53
	v_exp_f32_e32 v147, v16
	v_fmamk_f32 v16, v28, 0x3e38aa3b, v52
	v_add_u32_e32 v174, s4, v72
	v_add_u32_e32 v248, 0x10000, v175
	v_sub_u32_e32 v249, v179, v175
	v_sub_u32_e32 v250, v180, v175
	s_lshl_b64 s[4:5], s[28:29], 7
	v_exp_f32_e32 v149, v16
	v_fmamk_f32 v16, v29, 0x3e38aa3b, v52
	s_add_u32 s4, s4, s94
	v_exp_f32_e32 v151, v16
	v_fmamk_f32 v16, v30, 0x3e38aa3b, v52
	s_addc_u32 s5, s5, s92
	v_exp_f32_e32 v161, v16
	v_lshl_add_u64 v[16:17], s[4:5], 0, v[50:51]
	v_and_b32_e32 v18, 7, v168
	v_pk_fma_f32 v[124:125], v[46:47], s[44:45], v[52:53] op_sel_hi:[1,0,0]
	v_pk_fma_f32 v[130:131], v[44:45], s[44:45], v[52:53] op_sel_hi:[1,0,0]
	v_pk_fma_f32 v[134:135], v[42:43], s[44:45], v[52:53] op_sel_hi:[1,0,0]
	v_pk_fma_f32 v[126:127], v[40:41], s[44:45], v[52:53] op_sel_hi:[1,0,0]
	v_pk_fma_f32 v[128:129], v[38:39], s[44:45], v[52:53] op_sel_hi:[1,0,0]
	v_pk_fma_f32 v[132:133], v[36:37], s[44:45], v[52:53] op_sel_hi:[1,0,0]
	v_pk_fma_f32 v[136:137], v[34:35], s[44:45], v[52:53] op_sel_hi:[1,0,0]
	v_pk_fma_f32 v[138:139], v[32:33], s[44:45], v[52:53] op_sel_hi:[1,0,0]
	v_fmac_f32_e32 v52, 0x3e38aa3b, v31
	v_lshl_or_b32 v16, v18, 4, v16
	v_exp_f32_e32 v193, v52
	v_lshl_add_u64 v[156:157], s[54:55], 0, v[16:17]
	v_mad_u64_u32 v[16:17], s[4:5], s33, v252, v[48:49]
	s_waitcnt vmcnt(3)
	v_lshl_or_b32 v16, v164, 4, v16
	s_waitcnt vmcnt(5)
	ds_write_b128 v179, v[56:59] offset:16384
	s_waitcnt vmcnt(4)
	ds_write_b128 v180, v[60:63] offset:16384
	s_waitcnt vmcnt(3)
	ds_write_b128 v186, v[64:67] offset:40960
	v_cndmask_b32_e64 v189, v53, 1.0, vcc
	v_lshl_add_u64 v[158:159], s[54:55], 0, v[16:17]
	v_mov_b64_e32 v[62:63], v[14:15]
	v_mov_b64_e32 v[46:47], v[14:15]
	v_mov_b64_e32 v[30:31], v[14:15]
	v_mov_b64_e32 v[60:61], v[12:13]
	v_mov_b64_e32 v[58:59], v[10:11]
	v_mov_b64_e32 v[56:57], v[8:9]
	v_mov_b64_e32 v[54:55], v[6:7]
	v_mov_b64_e32 v[52:53], v[4:5]
	v_mov_b64_e32 v[50:51], v[2:3]
	v_mov_b64_e32 v[48:49], v[0:1]
	v_mov_b64_e32 v[44:45], v[12:13]
	v_mov_b64_e32 v[42:43], v[10:11]
	v_mov_b64_e32 v[40:41], v[8:9]
	v_mov_b64_e32 v[38:39], v[6:7]
	v_mov_b64_e32 v[36:37], v[4:5]
	v_mov_b64_e32 v[34:35], v[2:3]
	v_mov_b64_e32 v[32:33], v[0:1]
	v_mov_b64_e32 v[28:29], v[12:13]
	v_mov_b64_e32 v[26:27], v[10:11]
	v_mov_b64_e32 v[24:25], v[8:9]
	v_mov_b64_e32 v[22:23], v[6:7]
	v_mov_b64_e32 v[20:21], v[4:5]
	v_mov_b64_e32 v[18:19], v[2:3]
	v_mov_b64_e32 v[16:17], v[0:1]
	s_waitcnt lgkmcnt(0)
	s_barrier
.LBB0_1085:
	ds_read_b128 v[64:67], v181 offset:40960
	ds_read_b128 v[68:71], v181 offset:45056
	v_exp_f32_e32 v194, v136
	v_add_f32_e32 v136, 0, v144
	v_add_f32_e32 v136, v146, v136
	s_waitcnt lgkmcnt(1)
	v_mfma_f32_32x32x16_bf16 v[80:95], v[64:67], v[108:111], 0
	v_add_f32_e32 v136, v148, v136
	v_add_f32_e32 v136, v150, v136
	v_add_f32_e32 v136, v160, v136
	ds_read_b128 v[198:201], v187 offset:40960
	ds_read_b128 v[202:205], v187 offset:45056
	v_add_f32_e32 v136, v162, v136
	v_add_f32_e32 v136, v163, v136
	v_add_f32_e32 v136, v196, v136
	s_waitcnt lgkmcnt(2)
	v_mfma_f32_32x32x16_bf16 v[64:79], v[68:71], v[108:111], 0
	v_add_f32_e32 v136, v142, v136
	v_add_f32_e32 v136, v143, v136
	v_add_f32_e32 v136, v145, v136
	v_add_f32_e32 v136, v147, v136
	v_exp_f32_e32 v141, v138
	v_add_f32_e32 v136, v149, v136
	v_exp_f32_e32 v192, v139
	s_waitcnt lgkmcnt(1)
	v_mfma_f32_32x32x16_bf16 v[80:95], v[198:201], v[100:103], v[80:95]
	v_add_f32_e32 v136, v151, v136
	v_add_f32_e32 v136, v161, v136
	v_exp_f32_e32 v195, v137
	v_add_f32_e32 v136, v193, v136
	v_exp_f32_e32 v132, v132
	v_add_f32_e32 v136, v141, v136
	v_exp_f32_e32 v133, v133
	s_waitcnt lgkmcnt(0)
	v_mfma_f32_32x32x16_bf16 v[64:79], v[202:205], v[100:103], v[64:79]
	ds_read_b128 v[198:201], v188 offset:40960
	ds_read_b128 v[202:205], v188 offset:45056
	v_add_f32_e32 v136, v192, v136
	v_exp_f32_e32 v128, v128
	v_add_f32_e32 v136, v194, v136
	v_exp_f32_e32 v129, v129
	v_add_f32_e32 v136, v195, v136
	v_exp_f32_e32 v126, v126
	s_waitcnt lgkmcnt(1)
	v_mfma_f32_32x32x16_bf16 v[80:95], v[198:201], v[96:99], v[80:95]
	v_add_f32_e32 v136, v132, v136
	v_exp_f32_e32 v127, v127
	v_add_f32_e32 v136, v133, v136
	v_exp_f32_e32 v134, v134
	v_add_f32_e32 v136, v128, v136
	v_exp_f32_e32 v135, v135
	v_add_f32_e32 v136, v129, v136
	s_waitcnt lgkmcnt(0)
	v_mfma_f32_32x32x16_bf16 v[64:79], v[202:205], v[96:99], v[64:79]
	ds_read_b128 v[198:201], v176 offset:40960
	ds_read_b128 v[202:205], v176 offset:45056
	v_exp_f32_e32 v130, v130
	v_add_f32_e32 v136, v126, v136
	v_exp_f32_e32 v131, v131
	v_add_f32_e32 v136, v127, v136
	v_exp_f32_e32 v124, v124
	v_add_f32_e32 v136, v134, v136
	s_waitcnt lgkmcnt(1)
	v_mfma_f32_32x32x16_bf16 v[80:95], v[198:201], v[104:107], v[80:95]
	v_exp_f32_e32 v125, v125
	v_add_f32_e32 v136, v135, v136
	v_add_f32_e32 v136, v130, v136
	v_add_f32_e32 v136, v131, v136
	v_add_f32_e32 v136, v124, v136
	v_add_f32_e32 v190, v125, v136
	v_mov_b32_e32 v191, v190
	s_waitcnt lgkmcnt(0)
	v_mfma_f32_32x32x16_bf16 v[64:79], v[202:205], v[104:107], v[64:79]
	v_cvt_pk_bf16_f32 v136, v144, v146
	v_cvt_pk_bf16_f32 v138, v160, v162
	v_cvt_pk_bf16_f32 v142, v142, v143
	v_cvt_pk_bf16_f32 v143, v145, v147
	v_cvt_pk_bf16_f32 v146, v141, v192
	v_cvt_pk_bf16_f32 v147, v194, v195
	v_cvt_pk_bf16_f32 v192, v126, v127
	v_cvt_pk_bf16_f32 v194, v130, v131
	v_permlane32_swap_b32_e32 v190, v191
	v_cvt_pk_bf16_f32 v137, v148, v150
	v_cvt_pk_bf16_f32 v139, v163, v196
	v_permlane32_swap_b32_e32 v136, v138
	v_cvt_pk_bf16_f32 v144, v149, v151
	v_cvt_pk_bf16_f32 v145, v161, v193
	v_cvt_pk_bf16_f32 v148, v132, v133
	v_cvt_pk_bf16_f32 v149, v128, v129
	v_cvt_pk_bf16_f32 v193, v134, v135
	v_cvt_pk_bf16_f32 v195, v124, v125
	v_permlane32_swap_b32_e32 v192, v194
	v_permlane32_swap_b32_e32 v137, v139
	v_permlane32_swap_b32_e32 v142, v144
	v_permlane32_swap_b32_e32 v143, v145
	v_permlane32_swap_b32_e32 v146, v148
	v_permlane32_swap_b32_e32 v147, v149
	v_permlane32_swap_b32_e32 v193, v195
	v_lshl_add_u64 v[160:161], v[158:159], 0, s[30:31]
	v_add_co_u32_e32 v124, vcc, s39, v160
	s_mov_b32 s4, 0x186c0000
	s_nop 0
	v_addc_co_u32_e32 v125, vcc, 0, v161, vcc
	v_add_co_u32_e32 v128, vcc, s4, v160
	v_lshl_add_u64 v[162:163], v[156:157], 0, s[30:31]
	s_nop 0
	v_addc_co_u32_e32 v129, vcc, 0, v161, vcc
	v_add_co_u32_e32 v132, vcc, s39, v162
	global_load_dwordx4 v[124:127], v[124:125], off offset:3072
	s_nop 0
	global_load_dwordx4 v[128:131], v[128:129], off offset:3072
	v_addc_co_u32_e32 v133, vcc, 0, v163, vcc
	global_load_dwordx4 v[132:135], v[132:133], off offset:1536
	ds_read_b64_tr_b16 v[196:197], v175 offset:0
	ds_read_b64_tr_b16 v[198:199], v175 offset:0x800
	ds_read_b64_tr_b16 v[200:201], v175 offset:0x1000
	ds_read_b64_tr_b16 v[202:203], v175 offset:0x1800
	ds_read_b64_tr_b16 v[204:205], v175 offset:0x2000
	ds_read_b64_tr_b16 v[206:207], v175 offset:0x2800
	ds_read_b64_tr_b16 v[208:209], v175 offset:0x3000
	ds_read_b64_tr_b16 v[210:211], v175 offset:0x3800
	s_waitcnt lgkmcnt(0)
	s_nop 0
	v_mfma_f32_32x32x16_bf16 v[0:15], v[136:139], v[196:199], v[0:15]
	ds_read_b64_tr_b16 v[196:197], v175 offset:0x200
	ds_read_b64_tr_b16 v[198:199], v175 offset:0xa00
	v_mfma_f32_32x32x16_bf16 v[0:15], v[142:145], v[200:203], v[0:15]
	ds_read_b64_tr_b16 v[200:201], v175 offset:0x1200
	ds_read_b64_tr_b16 v[202:203], v175 offset:0x1a00
	v_mfma_f32_32x32x16_bf16 v[0:15], v[146:149], v[204:207], v[0:15]
	ds_read_b64_tr_b16 v[204:205], v175 offset:0x2200
	ds_read_b64_tr_b16 v[206:207], v175 offset:0x2a00
	v_mfma_f32_32x32x16_bf16 v[0:15], v[192:195], v[208:211], v[0:15]
	ds_read_b64_tr_b16 v[208:209], v175 offset:0x3200
	ds_read_b64_tr_b16 v[210:211], v175 offset:0x3a00
	s_waitcnt lgkmcnt(0)
	v_mfma_f32_32x32x16_bf16 v[48:63], v[136:139], v[196:199], v[48:63]
	ds_read_b64_tr_b16 v[196:197], v175 offset:0x400
	ds_read_b64_tr_b16 v[198:199], v175 offset:0xc00
	v_mfma_f32_32x32x16_bf16 v[48:63], v[142:145], v[200:203], v[48:63]
	ds_read_b64_tr_b16 v[200:201], v175 offset:0x1400
	ds_read_b64_tr_b16 v[202:203], v175 offset:0x1c00
	v_mfma_f32_32x32x16_bf16 v[48:63], v[146:149], v[204:207], v[48:63]
	ds_read_b64_tr_b16 v[204:205], v175 offset:0x2400
	ds_read_b64_tr_b16 v[206:207], v175 offset:0x2c00
	v_mfma_f32_32x32x16_bf16 v[48:63], v[192:195], v[208:211], v[48:63]
	ds_read_b64_tr_b16 v[208:209], v175 offset:0x3400
	ds_read_b64_tr_b16 v[210:211], v175 offset:0x3c00
	s_waitcnt lgkmcnt(0)
	v_mfma_f32_32x32x16_bf16 v[32:47], v[136:139], v[196:199], v[32:47]
	ds_read_b64_tr_b16 v[196:197], v175 offset:0x600
	ds_read_b64_tr_b16 v[198:199], v175 offset:0xe00
	v_mfma_f32_32x32x16_bf16 v[32:47], v[142:145], v[200:203], v[32:47]
	ds_read_b64_tr_b16 v[200:201], v175 offset:0x1600
	ds_read_b64_tr_b16 v[202:203], v175 offset:0x1e00
	v_mfma_f32_32x32x16_bf16 v[32:47], v[146:149], v[204:207], v[32:47]
	ds_read_b64_tr_b16 v[204:205], v175 offset:0x2600
	ds_read_b64_tr_b16 v[206:207], v175 offset:0x2e00
	v_mfma_f32_32x32x16_bf16 v[32:47], v[192:195], v[208:211], v[32:47]
	ds_read_b64_tr_b16 v[208:209], v175 offset:0x3600
	ds_read_b64_tr_b16 v[210:211], v175 offset:0x3e00
	s_waitcnt lgkmcnt(0)
	v_mfma_f32_32x32x16_bf16 v[16:31], v[136:139], v[196:199], v[16:31]
	v_max_f32_e32 v136, v81, v81
	v_max_f32_e32 v137, v80, v80
	v_max_f32_e32 v136, v137, v136
	v_max3_f32 v136, v136, v82, v83
	v_max3_f32 v136, v136, v84, v85
	v_max3_f32 v136, v136, v86, v87
	v_max3_f32 v136, v136, v88, v89
	v_max3_f32 v136, v136, v90, v91
	v_max3_f32 v136, v136, v92, v93
	v_mfma_f32_32x32x16_bf16 v[16:31], v[142:145], v[200:203], v[16:31]
	v_max3_f32 v136, v136, v94, v95
	v_max3_f32 v136, v136, v64, v65
	v_max3_f32 v136, v136, v66, v67
	v_max3_f32 v136, v136, v68, v69
	v_max3_f32 v136, v136, v70, v71
	v_max3_f32 v136, v136, v72, v73
	v_max3_f32 v136, v136, v74, v75
	v_max3_f32 v136, v136, v76, v77
	v_mfma_f32_32x32x16_bf16 v[16:31], v[146:149], v[204:207], v[16:31]
	v_max3_f32 v136, v136, v78, v79
	v_mov_b32_e32 v137, v136
	s_nop 1
	v_permlane32_swap_b32_e32 v136, v137
	v_max_f32_e32 v137, v137, v137
	v_max_f32_e32 v136, v136, v136
	v_max_f32_e32 v136, v136, v137
	v_sub_f32_e32 v137, v136, v140
	v_cmp_ge_f32_e32 vcc, s38, v137
	v_max_f32_e32 v137, v140, v140
	v_max_f32_e32 v136, v137, v136
	v_mfma_f32_32x32x16_bf16 v[16:31], v[192:195], v[208:211], v[16:31]
	v_sub_f32_e32 v137, v140, v136
	v_mul_f32_e32 v137, 0x3e38aa3b, v137
	v_exp_f32_e32 v137, v137
	s_cmp_eq_u64 vcc, exec
	s_cselect_b64 s[4:5], -1, 0
	s_waitcnt vmcnt(3)
	v_cndmask_b32_e64 v192, v137, 1.0, s[4:5]
	v_cmp_gt_f32_e32 vcc, 1.0, v192
	s_waitcnt vmcnt(3)
	v_add_u32_e32 v251, v249, v248
	ds_write_b128 v251, v[112:115]
	v_add_u32_e32 v251, v250, v248
	ds_write_b128 v251, v[116:119]
	ds_write_b128 v186, v[120:123] offset:32768
	s_cbranch_vccz .LBB0_1089
	s_and_saveexec_b64 s[8:9], s[6:7]
	ds_write_b32 v155, v192 offset:49280
	s_or_b64 exec, exec, s[8:9]
	s_waitcnt lgkmcnt(0)
	v_add_u32_e32 v137, v153, v178
	ds_read_b128 v[142:145], v137 offset:49376
	ds_read_b128 v[146:149], v137 offset:49344
	ds_read_b128 v[194:197], v137 offset:49312
	ds_read_b128 v[198:201], v137 offset:49280
	s_waitcnt lgkmcnt(3)
	v_pk_mul_f32 v[12:13], v[12:13], v[142:143]
	s_waitcnt lgkmcnt(2)
	v_pk_mul_f32 v[8:9], v[8:9], v[146:147]
	s_waitcnt lgkmcnt(1)
	v_pk_mul_f32 v[4:5], v[4:5], v[194:195]
	v_pk_mul_f32 v[14:15], v[14:15], v[144:145]
	v_pk_mul_f32 v[10:11], v[10:11], v[148:149]
	v_pk_mul_f32 v[6:7], v[6:7], v[196:197]
	s_waitcnt lgkmcnt(0)
	v_pk_mul_f32 v[2:3], v[2:3], v[200:201]
	v_pk_mul_f32 v[0:1], v[0:1], v[198:199]
	v_pk_mul_f32 v[60:61], v[60:61], v[142:143]
	v_pk_mul_f32 v[56:57], v[56:57], v[146:147]
	v_pk_mul_f32 v[52:53], v[52:53], v[194:195]
	v_pk_mul_f32 v[62:63], v[62:63], v[144:145]
	v_pk_mul_f32 v[58:59], v[58:59], v[148:149]
	v_pk_mul_f32 v[54:55], v[54:55], v[196:197]
	v_pk_mul_f32 v[50:51], v[50:51], v[200:201]
	v_pk_mul_f32 v[48:49], v[48:49], v[198:199]
	v_pk_mul_f32 v[44:45], v[44:45], v[142:143]
	v_pk_mul_f32 v[40:41], v[40:41], v[146:147]
	v_pk_mul_f32 v[36:37], v[36:37], v[194:195]
	v_pk_mul_f32 v[46:47], v[46:47], v[144:145]
	v_pk_mul_f32 v[42:43], v[42:43], v[148:149]
	v_pk_mul_f32 v[38:39], v[38:39], v[196:197]
	v_pk_mul_f32 v[34:35], v[34:35], v[200:201]
	v_pk_mul_f32 v[32:33], v[32:33], v[198:199]
	v_pk_mul_f32 v[28:29], v[28:29], v[142:143]
	v_pk_mul_f32 v[24:25], v[24:25], v[146:147]
	v_pk_mul_f32 v[20:21], v[20:21], v[194:195]
	v_pk_mul_f32 v[30:31], v[30:31], v[144:145]
	v_pk_mul_f32 v[26:27], v[26:27], v[148:149]
	v_pk_mul_f32 v[22:23], v[22:23], v[196:197]
	v_pk_mul_f32 v[18:19], v[18:19], v[200:201]
	v_pk_mul_f32 v[16:17], v[16:17], v[198:199]

.LBB0_1091:
	ds_read_b64_tr_b16 v[160:161], v174 offset:0
	ds_read_b64_tr_b16 v[162:163], v174 offset:0x800
	ds_read_b64_tr_b16 v[196:197], v174 offset:0x1000
	ds_read_b64_tr_b16 v[198:199], v174 offset:0x1800
	ds_read_b64_tr_b16 v[200:201], v174 offset:0x2000
	ds_read_b64_tr_b16 v[202:203], v174 offset:0x2800
	ds_read_b64_tr_b16 v[204:205], v174 offset:0x3000
	ds_read_b64_tr_b16 v[206:207], v174 offset:0x3800
	s_waitcnt lgkmcnt(0)
	s_nop 0
	v_mfma_f32_32x32x16_bf16 v[0:15], v[136:139], v[160:163], v[0:15]
	ds_read_b64_tr_b16 v[160:161], v174 offset:0x200
	ds_read_b64_tr_b16 v[162:163], v174 offset:0xa00
	v_mfma_f32_32x32x16_bf16 v[0:15], v[140:143], v[196:199], v[0:15]
	ds_read_b64_tr_b16 v[196:197], v174 offset:0x1200
	ds_read_b64_tr_b16 v[198:199], v174 offset:0x1a00
	v_mfma_f32_32x32x16_bf16 v[0:15], v[144:147], v[200:203], v[0:15]
	ds_read_b64_tr_b16 v[200:201], v174 offset:0x2200
	ds_read_b64_tr_b16 v[202:203], v174 offset:0x2a00
	v_mfma_f32_32x32x16_bf16 v[0:15], v[148:151], v[204:207], v[0:15]
	ds_read_b64_tr_b16 v[204:205], v174 offset:0x3200
	ds_read_b64_tr_b16 v[206:207], v174 offset:0x3a00
	s_waitcnt lgkmcnt(0)
	v_mfma_f32_32x32x16_bf16 v[48:63], v[136:139], v[160:163], v[48:63]
	ds_read_b64_tr_b16 v[160:161], v174 offset:0x400
	ds_read_b64_tr_b16 v[162:163], v174 offset:0xc00
	v_mfma_f32_32x32x16_bf16 v[48:63], v[140:143], v[196:199], v[48:63]
	ds_read_b64_tr_b16 v[196:197], v174 offset:0x1400
	ds_read_b64_tr_b16 v[198:199], v174 offset:0x1c00
	v_mfma_f32_32x32x16_bf16 v[48:63], v[144:147], v[200:203], v[48:63]
	ds_read_b64_tr_b16 v[200:201], v174 offset:0x2400
	ds_read_b64_tr_b16 v[202:203], v174 offset:0x2c00
	v_mfma_f32_32x32x16_bf16 v[48:63], v[148:151], v[204:207], v[48:63]
	ds_read_b64_tr_b16 v[204:205], v174 offset:0x3400
	ds_read_b64_tr_b16 v[206:207], v174 offset:0x3c00
	s_waitcnt lgkmcnt(0)
	v_mfma_f32_32x32x16_bf16 v[32:47], v[136:139], v[160:163], v[32:47]
	ds_read_b64_tr_b16 v[160:161], v174 offset:0x600
	ds_read_b64_tr_b16 v[162:163], v174 offset:0xe00
	v_mfma_f32_32x32x16_bf16 v[32:47], v[140:143], v[196:199], v[32:47]
	ds_read_b64_tr_b16 v[196:197], v174 offset:0x1600
	ds_read_b64_tr_b16 v[198:199], v174 offset:0x1e00
	v_mfma_f32_32x32x16_bf16 v[32:47], v[144:147], v[200:203], v[32:47]
	ds_read_b64_tr_b16 v[200:201], v174 offset:0x2600
	ds_read_b64_tr_b16 v[202:203], v174 offset:0x2e00
	v_mfma_f32_32x32x16_bf16 v[32:47], v[148:151], v[204:207], v[32:47]
	ds_read_b64_tr_b16 v[204:205], v174 offset:0x3600
	ds_read_b64_tr_b16 v[206:207], v174 offset:0x3e00
	s_waitcnt lgkmcnt(0)
	v_mfma_f32_32x32x16_bf16 v[16:31], v[136:139], v[160:163], v[16:31]
	v_max_f32_e32 v136, v81, v81
	v_max_f32_e32 v137, v80, v80
	v_max_f32_e32 v136, v137, v136
	v_max3_f32 v136, v136, v82, v83
	v_max3_f32 v136, v136, v84, v85
	v_max3_f32 v136, v136, v86, v87
	v_max3_f32 v136, v136, v88, v89
	v_max3_f32 v136, v136, v90, v91
	v_max3_f32 v136, v136, v92, v93
	v_mfma_f32_32x32x16_bf16 v[16:31], v[140:143], v[196:199], v[16:31]
	v_max3_f32 v136, v136, v94, v95
	v_max3_f32 v136, v136, v64, v65
	v_max3_f32 v136, v136, v66, v67
	v_max3_f32 v136, v136, v68, v69
	v_max3_f32 v136, v136, v70, v71
	v_max3_f32 v136, v136, v72, v73
	v_max3_f32 v136, v136, v74, v75
	v_max3_f32 v136, v136, v76, v77
	v_mfma_f32_32x32x16_bf16 v[16:31], v[144:147], v[200:203], v[16:31]
	v_max3_f32 v136, v136, v78, v79
	v_mov_b32_e32 v137, v136
	s_nop 1
	v_permlane32_swap_b32_e32 v136, v137
	v_max_f32_e32 v137, v137, v137
	v_max_f32_e32 v136, v136, v136
	v_max_f32_e32 v136, v136, v137
	v_sub_f32_e32 v137, v136, v193
	v_cmp_ge_f32_e32 vcc, s38, v137
	v_max_f32_e32 v137, v193, v193
	v_max_f32_e32 v136, v137, v136
	v_mfma_f32_32x32x16_bf16 v[16:31], v[148:151], v[204:207], v[16:31]
	v_sub_f32_e32 v137, v193, v136
	v_mul_f32_e32 v137, 0x3e38aa3b, v137
	v_exp_f32_e32 v137, v137
	s_cmp_eq_u64 vcc, exec
	s_cselect_b64 s[4:5], -1, 0
	s_waitcnt vmcnt(3)
	v_cndmask_b32_e64 v141, v137, 1.0, s[4:5]
	v_cmp_gt_f32_e32 vcc, 1.0, v141
	s_cmp_lg_u64 s[8:9], 0
	s_cbranch_scc0 .Lsw_da
	s_waitcnt vmcnt(0)
.Lsw_da:
	v_add_u32_e32 v251, v249, v175
	ds_write_b128 v251, v[124:127]
	v_add_u32_e32 v251, v250, v175
	ds_write_b128 v251, v[128:131]
	ds_write_b128 v186, v[132:135] offset:40960
	s_cbranch_vccz .LBB0_1095
	s_and_saveexec_b64 s[10:11], s[6:7]
	ds_write_b32 v155, v141 offset:49280
	s_or_b64 exec, exec, s[10:11]
	s_waitcnt lgkmcnt(0)
	v_add_u32_e32 v137, v153, v178
	ds_read_b128 v[124:127], v137 offset:49376
	ds_read_b128 v[128:131], v137 offset:49344
	ds_read_b128 v[132:135], v137 offset:49312
	ds_read_b128 v[142:145], v137 offset:49280
	s_waitcnt lgkmcnt(3)
	v_pk_mul_f32 v[12:13], v[12:13], v[124:125]
	s_waitcnt lgkmcnt(2)
	v_pk_mul_f32 v[8:9], v[8:9], v[128:129]
	s_waitcnt lgkmcnt(1)
	v_pk_mul_f32 v[4:5], v[4:5], v[132:133]
	v_pk_mul_f32 v[14:15], v[14:15], v[126:127]
	v_pk_mul_f32 v[10:11], v[10:11], v[130:131]
	v_pk_mul_f32 v[6:7], v[6:7], v[134:135]
	s_waitcnt lgkmcnt(0)
	v_pk_mul_f32 v[2:3], v[2:3], v[144:145]
	v_pk_mul_f32 v[0:1], v[0:1], v[142:143]
	v_pk_mul_f32 v[60:61], v[60:61], v[124:125]
	v_pk_mul_f32 v[56:57], v[56:57], v[128:129]
	v_pk_mul_f32 v[52:53], v[52:53], v[132:133]
	v_pk_mul_f32 v[62:63], v[62:63], v[126:127]
	v_pk_mul_f32 v[58:59], v[58:59], v[130:131]
	v_pk_mul_f32 v[54:55], v[54:55], v[134:135]
	v_pk_mul_f32 v[50:51], v[50:51], v[144:145]
	v_pk_mul_f32 v[48:49], v[48:49], v[142:143]
	v_pk_mul_f32 v[44:45], v[44:45], v[124:125]
	v_pk_mul_f32 v[40:41], v[40:41], v[128:129]
	v_pk_mul_f32 v[36:37], v[36:37], v[132:133]
	v_pk_mul_f32 v[46:47], v[46:47], v[126:127]
	v_pk_mul_f32 v[42:43], v[42:43], v[130:131]
	v_pk_mul_f32 v[38:39], v[38:39], v[134:135]
	v_pk_mul_f32 v[34:35], v[34:35], v[144:145]
	v_pk_mul_f32 v[32:33], v[32:33], v[142:143]
	v_pk_mul_f32 v[28:29], v[28:29], v[124:125]
	v_pk_mul_f32 v[24:25], v[24:25], v[128:129]
	v_pk_mul_f32 v[20:21], v[20:21], v[132:133]
	v_pk_mul_f32 v[30:31], v[30:31], v[126:127]
	v_pk_mul_f32 v[26:27], v[26:27], v[130:131]
	v_pk_mul_f32 v[22:23], v[22:23], v[134:135]
	v_pk_mul_f32 v[18:19], v[18:19], v[144:145]
	v_pk_mul_f32 v[16:17], v[16:17], v[142:143]
.LBB0_1095:
	v_cndmask_b32_e64 v140, v136, v193, s[4:5]
	v_mul_f32_e32 v124, 0xbe38aa3b, v140
	v_mov_b32_e32 v125, v124
	v_fmamk_f32 v80, v80, 0x3e38aa3b, v124
	v_fmamk_f32 v81, v81, 0x3e38aa3b, v124
	v_fmamk_f32 v82, v82, 0x3e38aa3b, v124
	v_fmamk_f32 v83, v83, 0x3e38aa3b, v124
	v_fmamk_f32 v84, v84, 0x3e38aa3b, v124
	v_fmamk_f32 v85, v85, 0x3e38aa3b, v124
	v_fmamk_f32 v86, v86, 0x3e38aa3b, v124
	v_fmamk_f32 v87, v87, 0x3e38aa3b, v124
	v_fmamk_f32 v88, v88, 0x3e38aa3b, v124
	v_fmamk_f32 v89, v89, 0x3e38aa3b, v124
	v_fmamk_f32 v90, v90, 0x3e38aa3b, v124
	v_fmamk_f32 v91, v91, 0x3e38aa3b, v124
	v_fmamk_f32 v92, v92, 0x3e38aa3b, v124
	v_fmamk_f32 v93, v93, 0x3e38aa3b, v124
	v_fmamk_f32 v94, v94, 0x3e38aa3b, v124
	v_fmac_f32_e32 v125, 0x3e38aa3b, v95
	v_exp_f32_e32 v144, v80
	v_exp_f32_e32 v146, v81
	v_exp_f32_e32 v148, v82
	v_exp_f32_e32 v150, v83
	v_exp_f32_e32 v160, v84
	v_exp_f32_e32 v162, v85
	v_exp_f32_e32 v163, v86
	v_exp_f32_e32 v196, v87
	v_exp_f32_e32 v142, v88
	v_exp_f32_e32 v143, v89
	v_exp_f32_e32 v145, v90
	v_exp_f32_e32 v147, v91
	v_exp_f32_e32 v149, v92
	v_exp_f32_e32 v151, v93
	v_exp_f32_e32 v161, v94
	v_exp_f32_e32 v193, v125
	v_pk_fma_f32 v[138:139], v[64:65], s[44:45], v[124:125] op_sel_hi:[1,0,0]
	v_add_f32_e32 v64, v190, v191
	v_fmac_f32_e32 v64, v189, v173
	v_add_f32_e32 v173, v194, v195
	v_pk_fma_f32 v[136:137], v[66:67], s[44:45], v[124:125] op_sel_hi:[1,0,0]
	v_pk_fma_f32 v[132:133], v[68:69], s[44:45], v[124:125] op_sel_hi:[1,0,0]
	v_pk_fma_f32 v[128:129], v[70:71], s[44:45], v[124:125] op_sel_hi:[1,0,0]
	v_pk_fma_f32 v[126:127], v[72:73], s[44:45], v[124:125] op_sel_hi:[1,0,0]
	v_pk_fma_f32 v[134:135], v[74:75], s[44:45], v[124:125] op_sel_hi:[1,0,0]
	v_pk_fma_f32 v[130:131], v[76:77], s[44:45], v[124:125] op_sel_hi:[1,0,0]
	v_pk_fma_f32 v[124:125], v[78:79], s[44:45], v[124:125] op_sel_hi:[1,0,0]
	v_fmac_f32_e32 v173, v64, v192
	v_lshl_add_u64 v[156:157], v[156:157], 0, s[0:1]
	v_lshl_add_u64 v[158:159], v[158:159], 0, s[0:1]
	s_add_i32 s46, s46, 2
	s_and_b64 vcc, exec, s[8:9]
	v_mov_b32_e32 v251, v174
	v_mov_b32_e32 v174, v175
	v_mov_b32_e32 v175, v248
	v_mov_b32_e32 v248, v251
	s_waitcnt lgkmcnt(0)
	s_barrier
	s_cbranch_vccnz .LBB0_1097
	v_mov_b32_e32 v189, v141
	s_branch .LBB0_1085

.LBB0_1104:
	s_and_b64 vcc, exec, s[8:9]
	s_cbranch_vccz .LBB0_1058
	s_lshl_b64 s[4:5], s[26:27], 13
	v_readlane_b32 s8, v253, 56
	v_readlane_b32 s9, v253, 57
	s_add_u32 s4, s8, s4
	s_addc_u32 s5, s9, s5
	s_lshl_b32 s90, s73, 7
	s_lshl_b32 s6, s73, 8
	s_add_u32 s4, s4, s6
	s_addc_u32 s5, s5, 0
	s_add_u32 s6, s8, s94
	s_addc_u32 s7, s9, s92
	s_cmp_gt_u32 s73, 2
	s_cselect_b32 s28, 0x100, 0
	s_add_u32 s6, s6, s28
	s_addc_u32 s7, s7, 0
	s_add_u32 s22, s6, 0x1c00
	v_add_u32_e32 v16, 32, v152
	s_addc_u32 s23, s7, 0
	v_ashrrev_i32_e32 v153, 31, v152
	v_ashrrev_i32_e32 v17, 31, v16
	s_add_u32 s20, s6, 0x1e00
	v_lshlrev_b32_e32 v22, 1, v172
	v_lshlrev_b64 v[48:49], 13, v[152:153]
	v_lshlrev_b64 v[8:9], 13, v[16:17]
	s_addc_u32 s21, s7, 0
	v_or_b32_e32 v50, v48, v22
	v_mov_b32_e32 v51, v49
	v_or_b32_e32 v8, v8, v22
	v_ashrrev_i32_e32 v155, 31, v154
	v_lshl_add_u64 v[0:1], s[20:21], 0, v[50:51]
	v_lshl_add_u64 v[4:5], s[20:21], 0, v[8:9]
	v_lshl_add_u64 v[10:11], s[22:23], 0, v[50:51]
	v_lshl_add_u64 v[12:13], s[22:23], 0, v[8:9]
	v_lshlrev_b64 v[18:19], 13, v[154:155]
	global_load_dwordx4 v[0:3], v[0:1], off
	s_nop 0
	global_load_dwordx4 v[4:7], v[4:5], off
	s_nop 0
	global_load_dwordx4 v[8:11], v[10:11], off
	s_nop 0
	global_load_dwordx4 v[12:15], v[12:13], off
	v_lshl_add_u64 v[18:19], s[4:5], 0, v[18:19]
	v_mov_b32_e32 v179, v177
	v_lshl_add_u64 v[18:19], v[18:19], 0, v[178:179]
	s_movk_i32 s30, 0x1000
	v_add_co_u32_e32 v20, vcc, s30, v18
	s_mov_b64 s[4:5], 0x1600
	s_nop 0
	v_addc_co_u32_e32 v21, vcc, 0, v19, vcc
	global_load_dwordx4 v[112:115], v[20:21], off offset:1536
	v_lshl_add_u64 v[18:19], v[18:19], 0, s[4:5]
	global_load_dwordx4 v[108:111], v[18:19], off offset:32
	global_load_dwordx4 v[120:123], v[18:19], off offset:64
	global_load_dwordx4 v[124:127], v[18:19], off offset:96
	global_load_dwordx4 v[116:119], v[18:19], off offset:128
	global_load_dwordx4 v[104:107], v[18:19], off offset:160
	global_load_dwordx4 v[100:103], v[18:19], off offset:192
	global_load_dwordx4 v[96:99], v[18:19], off offset:224
	v_and_b32_e32 v17, 0xfffff0, v152
	v_lshlrev_b32_e32 v20, 1, v152
	v_lshrrev_b32_e32 v21, 1, v152
	v_and_b32_e32 v23, 3, v152
	v_and_or_b32 v17, v20, 8, v17
	v_and_or_b32 v20, v21, 4, v23
	v_and_b32_e32 v23, 0xfffff0, v16
	v_lshlrev_b32_e32 v26, 1, v16
	v_lshlrev_b32_e32 v24, 8, v152
	v_and_b32_e32 v25, 0x70, v168
	v_lshlrev_b32_e32 v16, 8, v16
	v_lshrrev_b32_e32 v17, 1, v17
	v_and_or_b32 v23, v26, 8, v23
	v_and_b32_e32 v21, 48, v22
	v_bitop3_b32 v24, v22, v24, v25 bitop3:0xde
	v_bitop3_b32 v16, v22, v16, v25 bitop3:0xde
	v_or_b32_e32 v17, v17, v171
	v_lshrrev_b32_e32 v22, 1, v23
	v_lshlrev_b32_e32 v68, 8, v184
	v_and_b32_e32 v69, 0x70, v170
	v_lshlrev_b32_e32 v20, 6, v20
	v_add_u32_e32 v191, 0, v16
	v_lshlrev_b32_e32 v16, 9, v17
	v_or_b32_e32 v17, v22, v171
	v_bitop3_b32 v27, v178, v68, v69 bitop3:0xde
	v_or3_b32 v16, v16, v20, v21
	v_lshlrev_b32_e32 v17, 9, v17
	v_add_u32_e32 v189, 0, v27
	v_or3_b32 v17, v17, v20, v21
	v_add_u32_e32 v192, 0, v16
	v_add_u32_e32 v190, 0, v24
	v_add_u32_e32 v193, 0, v17
	s_waitcnt vmcnt(0)
	s_mov_b64 s[4:5], 0x80000
	v_and_b32_e32 v70, 0x100, v169
	s_mov_b32 s6, s91
	s_mov_b32 s7, s91
	s_mov_b32 s8, s91
	s_mov_b32 s9, s91
	s_mov_b32 s10, s91
	s_mov_b32 s11, s91
	s_mov_b32 s12, s91
	s_mov_b32 s13, s91
	s_mov_b32 s14, s91
	s_mov_b32 s15, s91
	s_waitcnt vmcnt(0)
	ds_write_b128 v192, v[0:3]
	ds_write_b128 v193, v[4:7]
	ds_write_b128 v190, v[8:11] offset:32768
	ds_write_b128 v191, v[12:15] offset:32768
	s_waitcnt lgkmcnt(0)
	s_barrier
	ds_read_b128 v[0:3], v189 offset:32768
	ds_read_b128 v[4:7], v189 offset:40960
	s_waitcnt lgkmcnt(1)
	v_mfma_f32_32x32x16_bf16 v[16:31], v[0:3], v[112:115], 0
	v_or_b32_e32 v0, 32, v178
	v_bitop3_b32 v0, v0, v68, v69 bitop3:0xde
	v_add_u32_e32 v198, 0, v0
	v_and_b32_e32 v8, 0xc0, v170
	v_and_or_b32 v71, v169, 24, v8
	v_lshl_add_u64 v[8:9], v[50:51], 0, s[4:5]
	s_mov_b64 s[4:5], 0xc0000
	s_waitcnt lgkmcnt(0)
	v_mfma_f32_32x32x16_bf16 v[32:47], v[4:7], v[112:115], 0
	ds_read_b128 v[0:3], v198 offset:32768
	ds_read_b128 v[4:7], v198 offset:40960
	v_lshl_add_u64 v[10:11], v[50:51], 0, s[4:5]
	v_lshl_add_u64 v[12:13], s[22:23], 0, v[8:9]
	v_lshl_add_u64 v[8:9], s[20:21], 0, v[8:9]
	v_lshl_add_u64 v[14:15], s[22:23], 0, v[10:11]
	v_lshl_add_u64 v[10:11], s[20:21], 0, v[10:11]
	v_or3_b32 v74, v71, v167, v70
	s_waitcnt lgkmcnt(1)
	v_mfma_f32_32x32x16_bf16 v[16:31], v[0:3], v[108:111], v[16:31]
	v_or_b32_e32 v0, 64, v178
	v_bitop3_b32 v0, v0, v68, v69 bitop3:0xde
	v_add_u32_e32 v197, 0, v0
	s_add_i32 s4, 0, 0x10000
	v_lshl_add_u32 v176, v166, 2, s4
	s_mov_b32 s4, s91
	s_mov_b32 s5, s91
	s_waitcnt lgkmcnt(0)
	v_mfma_f32_32x32x16_bf16 v[32:47], v[4:7], v[108:111], v[32:47]
	ds_read_b128 v[0:3], v197 offset:32768
	ds_read_b128 v[4:7], v197 offset:40960
	s_mov_b32 s16, s91
	s_mov_b32 s17, s91
	s_mov_b32 s18, s91
	s_mov_b32 s19, s91
	s_cmp_lg_u32 0, -1
	s_cselect_b32 s29, 0, 0
	s_waitcnt lgkmcnt(1)
	v_mfma_f32_32x32x16_bf16 v[16:31], v[0:3], v[120:123], v[16:31]
	v_or_b32_e32 v0, 0x60, v178
	v_bitop3_b32 v0, v0, v68, v69 bitop3:0xde
	v_add_u32_e32 v195, 0, v0
	s_lshr_b32 s27, s72, 6
	v_add_u32_e32 v188, s29, v74
	s_mov_b32 s26, 2
	v_lshl_add_u32 v179, v184, 2, v176
	s_waitcnt lgkmcnt(0)
	v_mfma_f32_32x32x16_bf16 v[32:47], v[4:7], v[120:123], v[32:47]
	ds_read_b128 v[0:3], v195 offset:32768
	ds_read_b128 v[4:7], v195 offset:40960
	v_mov_b32_e32 v186, 0
	s_waitcnt lgkmcnt(1)
	v_mfma_f32_32x32x16_bf16 v[16:31], v[0:3], v[124:127], v[16:31]
	v_or_b32_e32 v0, 0x80, v178
	v_bitop3_b32 v0, v0, v68, v69 bitop3:0xde
	v_add_u32_e32 v194, 0, v0
	ds_read_b128 v[0:3], v194 offset:32768
	s_waitcnt lgkmcnt(1)
	v_mfma_f32_32x32x16_bf16 v[32:47], v[4:7], v[124:127], v[32:47]
	ds_read_b128 v[4:7], v194 offset:40960
	s_waitcnt lgkmcnt(1)
	v_mfma_f32_32x32x16_bf16 v[16:31], v[0:3], v[116:119], v[16:31]
	v_or_b32_e32 v0, 0xa0, v178
	v_bitop3_b32 v0, v0, v68, v69 bitop3:0xde
	v_add_u32_e32 v196, 0, v0
	ds_read_b128 v[0:3], v196 offset:32768
	s_waitcnt lgkmcnt(1)
	v_mfma_f32_32x32x16_bf16 v[32:47], v[4:7], v[116:119], v[32:47]
	ds_read_b128 v[4:7], v196 offset:40960
	global_load_dwordx4 v[52:55], v[8:9], off
	global_load_dwordx4 v[56:59], v[10:11], off
	global_load_dwordx4 v[60:63], v[12:13], off
	global_load_dwordx4 v[64:67], v[14:15], off
	s_waitcnt lgkmcnt(1)
	v_mfma_f32_32x32x16_bf16 v[16:31], v[0:3], v[104:107], v[16:31]
	v_or_b32_e32 v0, 0xc0, v178
	v_bitop3_b32 v0, v0, v68, v69 bitop3:0xde
	v_add_u32_e32 v200, 0, v0
	ds_read_b128 v[0:3], v200 offset:32768
	s_waitcnt lgkmcnt(1)
	v_mfma_f32_32x32x16_bf16 v[32:47], v[4:7], v[104:107], v[32:47]
	ds_read_b128 v[4:7], v200 offset:40960
	s_waitcnt lgkmcnt(1)
	v_mfma_f32_32x32x16_bf16 v[16:31], v[0:3], v[100:103], v[16:31]
	v_or_b32_e32 v0, 0xe0, v178
	v_bitop3_b32 v0, v0, v68, v69 bitop3:0xde
	v_add_u32_e32 v199, 0, v0
	ds_read_b128 v[0:3], v199 offset:32768
	ds_read_b128 v[68:71], v199 offset:40960
	s_waitcnt lgkmcnt(2)
	v_mfma_f32_32x32x16_bf16 v[32:47], v[4:7], v[100:103], v[32:47]
	s_waitcnt lgkmcnt(1)
	v_mfma_f32_32x32x16_bf16 v[16:31], v[0:3], v[96:99], v[16:31]
	v_mov_b64_e32 v[0:1], s[4:5]
	v_mov_b64_e32 v[2:3], s[6:7]
	v_mov_b64_e32 v[4:5], s[8:9]
	v_mov_b64_e32 v[6:7], s[10:11]
	v_mov_b64_e32 v[8:9], s[12:13]
	v_mov_b64_e32 v[10:11], s[14:15]
	v_mov_b64_e32 v[12:13], s[16:17]
	s_waitcnt lgkmcnt(0)
	v_mfma_f32_32x32x16_bf16 v[32:47], v[68:71], v[96:99], v[32:47]
	s_nop 2
	v_max_f32_e32 v68, v17, v17
	v_max_f32_e32 v69, v16, v16
	v_max_f32_e32 v68, v69, v68
	v_max3_f32 v68, v68, v18, v19
	v_max3_f32 v68, v68, v20, v21
	v_max3_f32 v68, v68, v22, v23
	v_max3_f32 v68, v68, v24, v25
	v_max3_f32 v68, v68, v26, v27
	v_max3_f32 v68, v68, v28, v29
	v_max3_f32 v68, v68, v30, v31
	v_max3_f32 v68, v68, v32, v33
	v_max3_f32 v68, v68, v34, v35
	v_max3_f32 v68, v68, v36, v37
	v_max3_f32 v68, v68, v38, v39
	v_max3_f32 v68, v68, v40, v41
	v_max3_f32 v68, v68, v42, v43
	v_mov_b64_e32 v[14:15], s[18:19]
	v_max3_f32 v68, v68, v44, v45
	s_mov_b64 s[4:5], 0x140000
	v_max3_f32 v75, v68, v46, v47
	v_lshl_add_u64 v[68:69], v[50:51], 0, s[4:5]
	v_lshl_add_u64 v[70:71], s[22:23], 0, v[68:69]
	v_lshl_add_u64 v[50:51], v[50:51], 0, s[0:1]
	v_lshl_add_u64 v[68:69], s[20:21], 0, v[68:69]
	v_lshl_add_u64 v[72:73], s[22:23], 0, v[50:51]
	global_load_dwordx4 v[132:135], v[70:71], off
	global_load_dwordx4 v[128:131], v[72:73], off
	v_lshl_add_u64 v[50:51], s[20:21], 0, v[50:51]
	global_load_dwordx4 v[140:143], v[68:69], off
	global_load_dwordx4 v[136:139], v[50:51], off
	v_mov_b32_e32 v50, v75
	s_nop 1
	v_permlane32_swap_b32_e32 v75, v50
	v_max_f32_e32 v50, v50, v50
	v_max_f32_e32 v51, v75, v75
	v_max_f32_e32 v50, v51, v50
	v_add_f32_e32 v51, 0x7149f2ca, v50
	v_cmp_ge_f32_e32 vcc, s42, v51
	s_cmp_eq_u64 vcc, exec
	v_max_f32_e32 v50, 0xf149f2ca, v50
	s_cselect_b64 vcc, -1, 0
	v_cndmask_b32_e32 v166, v50, v227, vcc
	v_sub_f32_e32 v51, 0xf149f2ca, v50
	v_mul_f32_e32 v50, 0xbe0293ee, v166
	v_fmamk_f32 v16, v16, 0x3e0293ee, v50
	v_exp_f32_e32 v161, v16
	v_fmamk_f32 v16, v17, 0x3e0293ee, v50
	v_exp_f32_e32 v162, v16
	v_fmamk_f32 v16, v18, 0x3e0293ee, v50
	v_exp_f32_e32 v163, v16
	v_fmamk_f32 v16, v19, 0x3e0293ee, v50
	v_exp_f32_e32 v205, v16
	v_fmamk_f32 v16, v20, 0x3e0293ee, v50
	v_exp_f32_e32 v209, v16
	v_fmamk_f32 v16, v21, 0x3e0293ee, v50
	v_exp_f32_e32 v210, v16
	v_fmamk_f32 v16, v22, 0x3e0293ee, v50
	v_exp_f32_e32 v175, v16
	v_fmamk_f32 v16, v23, 0x3e0293ee, v50
	v_exp_f32_e32 v208, v16
	v_fmamk_f32 v16, v24, 0x3e0293ee, v50
	v_exp_f32_e32 v167, v16
	v_fmamk_f32 v16, v25, 0x3e0293ee, v50
	v_exp_f32_e32 v169, v16
	v_fmamk_f32 v16, v26, 0x3e0293ee, v50
	v_mul_f32_e32 v51, 0x3e0293ee, v51
	v_exp_f32_e32 v171, v16
	v_fmamk_f32 v16, v27, 0x3e0293ee, v50
	v_exp_f32_e32 v51, v51
	v_exp_f32_e32 v173, v16
	v_fmamk_f32 v16, v28, 0x3e0293ee, v50
	v_exp_f32_e32 v168, v16
	v_fmamk_f32 v16, v29, 0x3e0293ee, v50
	v_exp_f32_e32 v170, v16
	v_fmamk_f32 v16, v30, 0x3e0293ee, v50
	v_exp_f32_e32 v172, v16
	v_mad_u64_u32 v[16:17], s[4:5], s33, v252, v[48:49]
	v_pk_fma_f32 v[144:145], v[46:47], s[52:53], v[50:51] op_sel_hi:[1,0,0]
	v_pk_fma_f32 v[150:151], v[44:45], s[52:53], v[50:51] op_sel_hi:[1,0,0]
	v_pk_fma_f32 v[154:155], v[42:43], s[52:53], v[50:51] op_sel_hi:[1,0,0]
	v_pk_fma_f32 v[146:147], v[40:41], s[52:53], v[50:51] op_sel_hi:[1,0,0]
	v_pk_fma_f32 v[148:149], v[38:39], s[52:53], v[50:51] op_sel_hi:[1,0,0]
	v_pk_fma_f32 v[152:153], v[36:37], s[52:53], v[50:51] op_sel_hi:[1,0,0]
	v_pk_fma_f32 v[156:157], v[34:35], s[52:53], v[50:51] op_sel_hi:[1,0,0]
	v_pk_fma_f32 v[158:159], v[32:33], s[52:53], v[50:51] op_sel_hi:[1,0,0]
	v_fmac_f32_e32 v50, 0x3e0293ee, v31
	s_addk_i32 s29, 0x4000
	v_readlane_b32 s4, v254, 42
	v_exp_f32_e32 v174, v50
	s_add_u32 s4, s4, s28
	v_readlane_b32 s5, v254, 43
	s_waitcnt vmcnt(4)
	v_lshl_or_b32 v16, v164, 4, v16
	s_addc_u32 s5, s5, 0
	s_waitcnt vmcnt(7)
	ds_write_b128 v192, v[52:55] offset:16384
	s_waitcnt vmcnt(6)
	ds_write_b128 v193, v[56:59] offset:16384
	s_waitcnt vmcnt(5)
	ds_write_b128 v190, v[60:63] offset:49152
	s_waitcnt vmcnt(4)
	ds_write_b128 v191, v[64:67] offset:49152
	v_cndmask_b32_e64 v201, v51, 1.0, vcc
	v_lshl_add_u64 v[180:181], s[4:5], 0, v[16:17]
	v_mov_b64_e32 v[62:63], v[14:15]
	v_mov_b64_e32 v[46:47], v[14:15]
	v_mov_b64_e32 v[30:31], v[14:15]
	v_cmp_gt_u32_e64 s[6:7], 32, v165
	v_add_u32_e32 v187, s29, v74
	v_add_u32_e32 v248, 0x14000, v188
	v_sub_u32_e32 v249, v192, v188
	v_sub_u32_e32 v250, v193, v188
	v_mov_b64_e32 v[60:61], v[12:13]
	v_mov_b64_e32 v[58:59], v[10:11]
	v_mov_b64_e32 v[56:57], v[8:9]
	v_mov_b64_e32 v[54:55], v[6:7]
	v_mov_b64_e32 v[52:53], v[4:5]
	v_mov_b64_e32 v[50:51], v[2:3]
	v_mov_b64_e32 v[48:49], v[0:1]
	v_mov_b64_e32 v[44:45], v[12:13]
	v_mov_b64_e32 v[42:43], v[10:11]
	v_mov_b64_e32 v[40:41], v[8:9]
	v_mov_b64_e32 v[38:39], v[6:7]
	v_mov_b64_e32 v[36:37], v[4:5]
	v_mov_b64_e32 v[34:35], v[2:3]
	v_mov_b64_e32 v[32:33], v[0:1]
	v_mov_b64_e32 v[28:29], v[12:13]
	v_mov_b64_e32 v[26:27], v[10:11]
	v_mov_b64_e32 v[24:25], v[8:9]
	v_mov_b64_e32 v[22:23], v[6:7]
	v_mov_b64_e32 v[20:21], v[4:5]
	v_mov_b64_e32 v[18:19], v[2:3]
	v_mov_b64_e32 v[16:17], v[0:1]
	s_waitcnt lgkmcnt(0)
	s_barrier
.LBB0_1106:
	ds_read_b128 v[64:67], v189 offset:49152
	ds_read_b128 v[68:71], v189 offset:57344
	ds_read_b128 v[232:235], v198 offset:49152
	ds_read_b128 v[236:239], v198 offset:57344
	v_add_f32_e32 v160, 0, v161
	v_add_f32_e32 v160, v162, v160
	s_waitcnt lgkmcnt(3)
	v_mfma_f32_32x32x16_bf16 v[80:95], v[64:67], v[112:115], 0
	v_add_f32_e32 v160, v163, v160
	v_add_f32_e32 v160, v205, v160
	v_add_f32_e32 v160, v209, v160
	v_add_f32_e32 v160, v210, v160
	v_add_f32_e32 v160, v175, v160
	v_add_f32_e32 v160, v208, v160
	v_add_f32_e32 v160, v167, v160
	s_waitcnt lgkmcnt(2)
	v_mfma_f32_32x32x16_bf16 v[64:79], v[68:71], v[112:115], 0
	v_add_f32_e32 v160, v169, v160
	v_add_f32_e32 v160, v171, v160
	v_add_f32_e32 v160, v173, v160
	v_exp_f32_e32 v158, v158
	v_add_f32_e32 v160, v168, v160
	v_exp_f32_e32 v159, v159
	v_add_f32_e32 v160, v170, v160
	s_waitcnt lgkmcnt(1)
	v_mfma_f32_32x32x16_bf16 v[80:95], v[232:235], v[108:111], v[80:95]
	v_exp_f32_e32 v156, v156
	v_add_f32_e32 v160, v172, v160
	v_exp_f32_e32 v157, v157
	v_add_f32_e32 v160, v174, v160
	v_exp_f32_e32 v152, v152
	v_add_f32_e32 v160, v158, v160
	v_exp_f32_e32 v153, v153
	s_waitcnt lgkmcnt(0)
	v_mfma_f32_32x32x16_bf16 v[64:79], v[236:239], v[108:111], v[64:79]
	ds_read_b128 v[232:235], v197 offset:49152
	ds_read_b128 v[236:239], v197 offset:57344
	v_add_f32_e32 v160, v159, v160
	v_exp_f32_e32 v148, v148
	v_add_f32_e32 v160, v156, v160
	v_exp_f32_e32 v149, v149
	v_add_f32_e32 v160, v157, v160
	v_exp_f32_e32 v146, v146
	s_waitcnt lgkmcnt(1)
	v_mfma_f32_32x32x16_bf16 v[80:95], v[232:235], v[120:123], v[80:95]
	v_add_f32_e32 v160, v152, v160
	v_exp_f32_e32 v147, v147
	v_add_f32_e32 v160, v153, v160
	v_exp_f32_e32 v154, v154
	v_add_f32_e32 v160, v148, v160
	v_exp_f32_e32 v155, v155
	v_add_f32_e32 v160, v149, v160
	s_waitcnt lgkmcnt(0)
	v_mfma_f32_32x32x16_bf16 v[64:79], v[236:239], v[120:123], v[64:79]
	ds_read_b128 v[232:235], v195 offset:49152
	ds_read_b128 v[236:239], v195 offset:57344
	v_exp_f32_e32 v150, v150
	v_add_f32_e32 v160, v146, v160
	v_exp_f32_e32 v151, v151
	v_add_f32_e32 v160, v147, v160
	v_exp_f32_e32 v144, v144
	v_add_f32_e32 v160, v154, v160
	s_waitcnt lgkmcnt(1)
	v_mfma_f32_32x32x16_bf16 v[80:95], v[232:235], v[124:127], v[80:95]
	v_exp_f32_e32 v145, v145
	v_add_f32_e32 v160, v155, v160
	v_add_f32_e32 v160, v150, v160
	v_add_f32_e32 v160, v151, v160
	v_add_f32_e32 v160, v144, v160
	v_add_f32_e32 v202, v145, v160
	v_mov_b32_e32 v203, v202
	s_waitcnt lgkmcnt(0)
	v_mfma_f32_32x32x16_bf16 v[64:79], v[236:239], v[124:127], v[64:79]
	ds_read_b128 v[232:235], v194 offset:49152
	ds_read_b128 v[236:239], v194 offset:57344
	v_cvt_pk_bf16_f32 v160, v161, v162
	v_cvt_pk_bf16_f32 v162, v209, v210
	v_cvt_pk_bf16_f32 v204, v167, v169
	v_cvt_pk_bf16_f32 v206, v168, v170
	v_permlane32_swap_b32_e32 v202, v203
	s_waitcnt lgkmcnt(1)
	v_mfma_f32_32x32x16_bf16 v[80:95], v[232:235], v[116:119], v[80:95]
	v_cvt_pk_bf16_f32 v161, v163, v205
	v_cvt_pk_bf16_f32 v163, v175, v208
	v_permlane32_swap_b32_e32 v160, v162
	v_cvt_pk_bf16_f32 v205, v171, v173
	v_cvt_pk_bf16_f32 v207, v172, v174
	v_permlane32_swap_b32_e32 v204, v206
	s_waitcnt lgkmcnt(0)
	v_mfma_f32_32x32x16_bf16 v[64:79], v[236:239], v[116:119], v[64:79]
	ds_read_b128 v[232:235], v196 offset:49152
	ds_read_b128 v[236:239], v196 offset:57344
	v_cvt_pk_bf16_f32 v168, v158, v159
	v_cvt_pk_bf16_f32 v169, v156, v157
	v_cvt_pk_bf16_f32 v170, v152, v153
	v_cvt_pk_bf16_f32 v171, v148, v149
	v_cvt_pk_bf16_f32 v172, v146, v147
	v_cvt_pk_bf16_f32 v173, v154, v155
	s_waitcnt lgkmcnt(1)
	v_mfma_f32_32x32x16_bf16 v[80:95], v[232:235], v[104:107], v[80:95]
	v_cvt_pk_bf16_f32 v174, v150, v151
	v_cvt_pk_bf16_f32 v175, v144, v145
	v_permlane32_swap_b32_e32 v161, v163
	v_permlane32_swap_b32_e32 v205, v207
	v_permlane32_swap_b32_e32 v168, v170
	s_waitcnt lgkmcnt(0)
	v_mfma_f32_32x32x16_bf16 v[64:79], v[236:239], v[104:107], v[64:79]
	ds_read_b128 v[232:235], v200 offset:49152
	ds_read_b128 v[236:239], v200 offset:57344
	v_permlane32_swap_b32_e32 v169, v171
	v_permlane32_swap_b32_e32 v172, v174
	v_permlane32_swap_b32_e32 v173, v175
	s_waitcnt lgkmcnt(1)
	v_mfma_f32_32x32x16_bf16 v[80:95], v[232:235], v[100:103], v[80:95]
	s_waitcnt lgkmcnt(0)
	v_mfma_f32_32x32x16_bf16 v[64:79], v[236:239], v[100:103], v[64:79]
	ds_read_b128 v[232:235], v199 offset:49152
	ds_read_b128 v[236:239], v199 offset:57344
	s_waitcnt lgkmcnt(1)
	v_mfma_f32_32x32x16_bf16 v[80:95], v[232:235], v[96:99], v[80:95]
	s_waitcnt lgkmcnt(0)
	v_mfma_f32_32x32x16_bf16 v[64:79], v[236:239], v[96:99], v[64:79]
	s_mov_b32 s4, 0xfff40000
	v_add_co_u32_e32 v148, vcc, s4, v180
	s_mov_b32 s4, 0xfff80000
	s_nop 0
	v_addc_co_u32_e32 v149, vcc, -1, v181, vcc
	v_add_co_u32_e32 v152, vcc, s4, v180
	s_nop 1
	v_addc_co_u32_e32 v153, vcc, -1, v181, vcc
	global_load_dwordx4 v[144:147], v[148:149], off
	s_nop 0
	global_load_dwordx4 v[148:151], v[148:149], off offset:-512
	s_nop 0
	global_load_dwordx4 v[156:159], v[152:153], off
	s_nop 0
	global_load_dwordx4 v[152:155], v[152:153], off offset:-512
	ds_read_b64_tr_b16 v[208:209], v188 offset:0
	ds_read_b64_tr_b16 v[210:211], v188 offset:0x800
	ds_read_b64_tr_b16 v[232:233], v188 offset:0x1000
	ds_read_b64_tr_b16 v[234:235], v188 offset:0x1800
	ds_read_b64_tr_b16 v[236:237], v188 offset:0x2000
	ds_read_b64_tr_b16 v[238:239], v188 offset:0x2800
	ds_read_b64_tr_b16 v[240:241], v188 offset:0x3000
	ds_read_b64_tr_b16 v[242:243], v188 offset:0x3800
	s_waitcnt lgkmcnt(0)
	s_nop 0
	v_mfma_f32_32x32x16_bf16 v[0:15], v[160:163], v[208:211], v[0:15]
	ds_read_b64_tr_b16 v[208:209], v188 offset:0x200
	ds_read_b64_tr_b16 v[210:211], v188 offset:0xa00
	v_mfma_f32_32x32x16_bf16 v[0:15], v[204:207], v[232:235], v[0:15]
	ds_read_b64_tr_b16 v[232:233], v188 offset:0x1200
	ds_read_b64_tr_b16 v[234:235], v188 offset:0x1a00
	v_mfma_f32_32x32x16_bf16 v[0:15], v[168:171], v[236:239], v[0:15]
	ds_read_b64_tr_b16 v[236:237], v188 offset:0x2200
	ds_read_b64_tr_b16 v[238:239], v188 offset:0x2a00
	v_mfma_f32_32x32x16_bf16 v[0:15], v[172:175], v[240:243], v[0:15]
	ds_read_b64_tr_b16 v[240:241], v188 offset:0x3200
	ds_read_b64_tr_b16 v[242:243], v188 offset:0x3a00
	s_waitcnt lgkmcnt(0)
	v_mfma_f32_32x32x16_bf16 v[48:63], v[160:163], v[208:211], v[48:63]
	ds_read_b64_tr_b16 v[208:209], v188 offset:0x400
	ds_read_b64_tr_b16 v[210:211], v188 offset:0xc00
	v_mfma_f32_32x32x16_bf16 v[48:63], v[204:207], v[232:235], v[48:63]
	ds_read_b64_tr_b16 v[232:233], v188 offset:0x1400
	ds_read_b64_tr_b16 v[234:235], v188 offset:0x1c00
	v_mfma_f32_32x32x16_bf16 v[48:63], v[168:171], v[236:239], v[48:63]
	ds_read_b64_tr_b16 v[236:237], v188 offset:0x2400
	ds_read_b64_tr_b16 v[238:239], v188 offset:0x2c00
	v_mfma_f32_32x32x16_bf16 v[48:63], v[172:175], v[240:243], v[48:63]
	ds_read_b64_tr_b16 v[240:241], v188 offset:0x3400
	ds_read_b64_tr_b16 v[242:243], v188 offset:0x3c00
	s_waitcnt lgkmcnt(0)
	v_mfma_f32_32x32x16_bf16 v[32:47], v[160:163], v[208:211], v[32:47]
	ds_read_b64_tr_b16 v[208:209], v188 offset:0x600
	ds_read_b64_tr_b16 v[210:211], v188 offset:0xe00
	v_mfma_f32_32x32x16_bf16 v[32:47], v[204:207], v[232:235], v[32:47]
	ds_read_b64_tr_b16 v[232:233], v188 offset:0x1600
	ds_read_b64_tr_b16 v[234:235], v188 offset:0x1e00
	v_mfma_f32_32x32x16_bf16 v[32:47], v[168:171], v[236:239], v[32:47]
	ds_read_b64_tr_b16 v[236:237], v188 offset:0x2600
	ds_read_b64_tr_b16 v[238:239], v188 offset:0x2e00
	v_mfma_f32_32x32x16_bf16 v[32:47], v[172:175], v[240:243], v[32:47]
	ds_read_b64_tr_b16 v[240:241], v188 offset:0x3600
	ds_read_b64_tr_b16 v[242:243], v188 offset:0x3e00
	s_waitcnt lgkmcnt(0)
	v_mfma_f32_32x32x16_bf16 v[16:31], v[160:163], v[208:211], v[16:31]
	v_max_f32_e32 v160, v81, v81
	v_max_f32_e32 v161, v80, v80
	v_max_f32_e32 v160, v161, v160
	v_max3_f32 v160, v160, v82, v83
	v_max3_f32 v160, v160, v84, v85
	v_max3_f32 v160, v160, v86, v87
	v_max3_f32 v160, v160, v88, v89
	v_max3_f32 v160, v160, v90, v91
	v_max3_f32 v160, v160, v92, v93
	v_mfma_f32_32x32x16_bf16 v[16:31], v[204:207], v[232:235], v[16:31]
	v_max3_f32 v160, v160, v94, v95
	v_max3_f32 v160, v160, v64, v65
	v_max3_f32 v160, v160, v66, v67
	v_max3_f32 v160, v160, v68, v69
	v_max3_f32 v160, v160, v70, v71
	v_max3_f32 v160, v160, v72, v73
	v_max3_f32 v160, v160, v74, v75
	v_max3_f32 v160, v160, v76, v77
	v_mfma_f32_32x32x16_bf16 v[16:31], v[168:171], v[236:239], v[16:31]
	v_max3_f32 v160, v160, v78, v79
	v_mov_b32_e32 v161, v160
	s_nop 1
	v_permlane32_swap_b32_e32 v160, v161
	v_max_f32_e32 v161, v161, v161
	v_max_f32_e32 v160, v160, v160
	v_max_f32_e32 v160, v160, v161
	v_sub_f32_e32 v161, v160, v166
	v_cmp_ge_f32_e32 vcc, s42, v161
	v_max_f32_e32 v161, v166, v166
	v_max_f32_e32 v160, v161, v160
	v_mfma_f32_32x32x16_bf16 v[16:31], v[172:175], v[240:243], v[16:31]
	v_sub_f32_e32 v161, v166, v160
	v_mul_f32_e32 v161, 0x3e0293ee, v161
	v_exp_f32_e32 v161, v161
	s_cmp_eq_u64 vcc, exec
	s_cselect_b64 s[4:5], -1, 0
	s_waitcnt vmcnt(4)
	v_cndmask_b32_e64 v204, v161, 1.0, s[4:5]
	v_cmp_gt_f32_e32 vcc, 1.0, v204
	s_waitcnt vmcnt(4)
	v_add_u32_e32 v251, v249, v248
	ds_write_b128 v251, v[136:139]
	v_add_u32_e32 v251, v250, v248
	ds_write_b128 v251, v[140:143]
	ds_write_b128 v190, v[128:131] offset:32768
	ds_write_b128 v191, v[132:135] offset:32768
	s_cbranch_vccz .LBB0_1110
	s_and_saveexec_b64 s[8:9], s[6:7]
	ds_write_b32 v179, v204 offset:128
	s_or_b64 exec, exec, s[8:9]
	s_waitcnt lgkmcnt(0)
	v_add_u32_e32 v161, v176, v178
	ds_read_b128 v[162:165], v161 offset:224
	ds_read_b128 v[168:171], v161 offset:192
	ds_read_b128 v[172:175], v161 offset:160
	ds_read_b128 v[206:209], v161 offset:128
	s_waitcnt lgkmcnt(3)
	v_pk_mul_f32 v[12:13], v[12:13], v[162:163]
	s_waitcnt lgkmcnt(2)
	v_pk_mul_f32 v[8:9], v[8:9], v[168:169]
	s_waitcnt lgkmcnt(1)
	v_pk_mul_f32 v[4:5], v[4:5], v[172:173]
	v_pk_mul_f32 v[14:15], v[14:15], v[164:165]
	v_pk_mul_f32 v[10:11], v[10:11], v[170:171]
	v_pk_mul_f32 v[6:7], v[6:7], v[174:175]
	s_waitcnt lgkmcnt(0)
	v_pk_mul_f32 v[2:3], v[2:3], v[208:209]
	v_pk_mul_f32 v[0:1], v[0:1], v[206:207]
	v_pk_mul_f32 v[60:61], v[60:61], v[162:163]
	v_pk_mul_f32 v[56:57], v[56:57], v[168:169]
	v_pk_mul_f32 v[52:53], v[52:53], v[172:173]
	v_pk_mul_f32 v[62:63], v[62:63], v[164:165]
	v_pk_mul_f32 v[58:59], v[58:59], v[170:171]
	v_pk_mul_f32 v[54:55], v[54:55], v[174:175]
	v_pk_mul_f32 v[50:51], v[50:51], v[208:209]
	v_pk_mul_f32 v[48:49], v[48:49], v[206:207]
	v_pk_mul_f32 v[44:45], v[44:45], v[162:163]
	v_pk_mul_f32 v[40:41], v[40:41], v[168:169]
	v_pk_mul_f32 v[36:37], v[36:37], v[172:173]
	v_pk_mul_f32 v[46:47], v[46:47], v[164:165]
	v_pk_mul_f32 v[42:43], v[42:43], v[170:171]
	v_pk_mul_f32 v[38:39], v[38:39], v[174:175]
	v_pk_mul_f32 v[34:35], v[34:35], v[208:209]
	v_pk_mul_f32 v[32:33], v[32:33], v[206:207]
	v_pk_mul_f32 v[28:29], v[28:29], v[162:163]
	v_pk_mul_f32 v[24:25], v[24:25], v[168:169]
	v_pk_mul_f32 v[20:21], v[20:21], v[172:173]
	v_pk_mul_f32 v[30:31], v[30:31], v[164:165]
	v_pk_mul_f32 v[26:27], v[26:27], v[170:171]
	v_pk_mul_f32 v[22:23], v[22:23], v[174:175]
	v_pk_mul_f32 v[18:19], v[18:19], v[208:209]
	v_pk_mul_f32 v[16:17], v[16:17], v[206:207]

.LBB0_1112:
	ds_read_b64_tr_b16 v[208:209], v187 offset:0
	ds_read_b64_tr_b16 v[210:211], v187 offset:0x800
	ds_read_b64_tr_b16 v[232:233], v187 offset:0x1000
	ds_read_b64_tr_b16 v[234:235], v187 offset:0x1800
	ds_read_b64_tr_b16 v[236:237], v187 offset:0x2000
	ds_read_b64_tr_b16 v[238:239], v187 offset:0x2800
	ds_read_b64_tr_b16 v[240:241], v187 offset:0x3000
	ds_read_b64_tr_b16 v[242:243], v187 offset:0x3800
	s_waitcnt lgkmcnt(0)
	s_nop 0
	v_mfma_f32_32x32x16_bf16 v[0:15], v[160:163], v[208:211], v[0:15]
	ds_read_b64_tr_b16 v[208:209], v187 offset:0x200
	ds_read_b64_tr_b16 v[210:211], v187 offset:0xa00
	v_mfma_f32_32x32x16_bf16 v[0:15], v[164:167], v[232:235], v[0:15]
	ds_read_b64_tr_b16 v[232:233], v187 offset:0x1200
	ds_read_b64_tr_b16 v[234:235], v187 offset:0x1a00
	v_mfma_f32_32x32x16_bf16 v[0:15], v[168:171], v[236:239], v[0:15]
	ds_read_b64_tr_b16 v[236:237], v187 offset:0x2200
	ds_read_b64_tr_b16 v[238:239], v187 offset:0x2a00
	v_mfma_f32_32x32x16_bf16 v[0:15], v[172:175], v[240:243], v[0:15]
	ds_read_b64_tr_b16 v[240:241], v187 offset:0x3200
	ds_read_b64_tr_b16 v[242:243], v187 offset:0x3a00
	s_waitcnt lgkmcnt(0)
	v_mfma_f32_32x32x16_bf16 v[48:63], v[160:163], v[208:211], v[48:63]
	ds_read_b64_tr_b16 v[208:209], v187 offset:0x400
	ds_read_b64_tr_b16 v[210:211], v187 offset:0xc00
	v_mfma_f32_32x32x16_bf16 v[48:63], v[164:167], v[232:235], v[48:63]
	ds_read_b64_tr_b16 v[232:233], v187 offset:0x1400
	ds_read_b64_tr_b16 v[234:235], v187 offset:0x1c00
	v_mfma_f32_32x32x16_bf16 v[48:63], v[168:171], v[236:239], v[48:63]
	ds_read_b64_tr_b16 v[236:237], v187 offset:0x2400
	ds_read_b64_tr_b16 v[238:239], v187 offset:0x2c00
	v_mfma_f32_32x32x16_bf16 v[48:63], v[172:175], v[240:243], v[48:63]
	ds_read_b64_tr_b16 v[240:241], v187 offset:0x3400
	ds_read_b64_tr_b16 v[242:243], v187 offset:0x3c00
	s_waitcnt lgkmcnt(0)
	v_mfma_f32_32x32x16_bf16 v[32:47], v[160:163], v[208:211], v[32:47]
	ds_read_b64_tr_b16 v[208:209], v187 offset:0x600
	ds_read_b64_tr_b16 v[210:211], v187 offset:0xe00
	v_mfma_f32_32x32x16_bf16 v[32:47], v[164:167], v[232:235], v[32:47]
	ds_read_b64_tr_b16 v[232:233], v187 offset:0x1600
	ds_read_b64_tr_b16 v[234:235], v187 offset:0x1e00
	v_mfma_f32_32x32x16_bf16 v[32:47], v[168:171], v[236:239], v[32:47]
	ds_read_b64_tr_b16 v[236:237], v187 offset:0x2600
	ds_read_b64_tr_b16 v[238:239], v187 offset:0x2e00
	v_mfma_f32_32x32x16_bf16 v[32:47], v[172:175], v[240:243], v[32:47]
	ds_read_b64_tr_b16 v[240:241], v187 offset:0x3600
	ds_read_b64_tr_b16 v[242:243], v187 offset:0x3e00
	s_waitcnt lgkmcnt(0)
	v_mfma_f32_32x32x16_bf16 v[16:31], v[160:163], v[208:211], v[16:31]
	v_max_f32_e32 v160, v81, v81
	v_max_f32_e32 v161, v80, v80
	v_max_f32_e32 v160, v161, v160
	v_max3_f32 v160, v160, v82, v83
	v_max3_f32 v160, v160, v84, v85
	v_max3_f32 v160, v160, v86, v87
	v_max3_f32 v160, v160, v88, v89
	v_max3_f32 v160, v160, v90, v91
	v_max3_f32 v160, v160, v92, v93
	v_mfma_f32_32x32x16_bf16 v[16:31], v[164:167], v[232:235], v[16:31]
	v_max3_f32 v160, v160, v94, v95
	v_max3_f32 v160, v160, v64, v65
	v_max3_f32 v160, v160, v66, v67
	v_max3_f32 v160, v160, v68, v69
	v_max3_f32 v160, v160, v70, v71
	v_max3_f32 v160, v160, v72, v73
	v_max3_f32 v160, v160, v74, v75
	v_max3_f32 v160, v160, v76, v77
	v_mfma_f32_32x32x16_bf16 v[16:31], v[168:171], v[236:239], v[16:31]
	v_max3_f32 v160, v160, v78, v79
	v_mov_b32_e32 v161, v160
	s_nop 1
	v_permlane32_swap_b32_e32 v160, v161
	v_max_f32_e32 v161, v161, v161
	v_max_f32_e32 v160, v160, v160
	v_max_f32_e32 v160, v160, v161
	v_sub_f32_e32 v161, v160, v205
	v_cmp_ge_f32_e32 vcc, s42, v161
	v_max_f32_e32 v161, v205, v205
	v_max_f32_e32 v161, v161, v160
	v_mfma_f32_32x32x16_bf16 v[16:31], v[172:175], v[240:243], v[16:31]
	v_sub_f32_e32 v160, v205, v161
	v_mul_f32_e32 v160, 0x3e0293ee, v160
	v_exp_f32_e32 v160, v160
	s_cmp_eq_u64 vcc, exec
	s_cselect_b64 s[4:5], -1, 0
	s_waitcnt vmcnt(4)
	v_cndmask_b32_e64 v160, v160, 1.0, s[4:5]
	v_cmp_gt_f32_e32 vcc, 1.0, v160
	s_cmp_lg_u64 s[8:9], 0
	s_cbranch_scc0 .Lsw_gqa
	s_waitcnt vmcnt(0)
.Lsw_gqa:
	v_add_u32_e32 v251, v249, v188
	ds_write_b128 v251, v[144:147]
	v_add_u32_e32 v251, v250, v188
	ds_write_b128 v251, v[156:159]
	ds_write_b128 v190, v[148:151] offset:49152
	ds_write_b128 v191, v[152:155] offset:49152
	s_cbranch_vccz .LBB0_1116
	s_and_saveexec_b64 s[10:11], s[6:7]
	ds_write_b32 v179, v160 offset:128
	s_or_b64 exec, exec, s[10:11]
	s_waitcnt lgkmcnt(0)
	v_add_u32_e32 v156, v176, v178
	ds_read_b128 v[144:147], v156 offset:224
	ds_read_b128 v[148:151], v156 offset:192
	ds_read_b128 v[152:155], v156 offset:160
	ds_read_b128 v[156:159], v156 offset:128
	s_waitcnt lgkmcnt(3)
	v_pk_mul_f32 v[12:13], v[12:13], v[144:145]
	s_waitcnt lgkmcnt(2)
	v_pk_mul_f32 v[8:9], v[8:9], v[148:149]
	s_waitcnt lgkmcnt(1)
	v_pk_mul_f32 v[4:5], v[4:5], v[152:153]
	v_pk_mul_f32 v[14:15], v[14:15], v[146:147]
	v_pk_mul_f32 v[10:11], v[10:11], v[150:151]
	v_pk_mul_f32 v[6:7], v[6:7], v[154:155]
	s_waitcnt lgkmcnt(0)
	v_pk_mul_f32 v[2:3], v[2:3], v[158:159]
	v_pk_mul_f32 v[0:1], v[0:1], v[156:157]
	v_pk_mul_f32 v[60:61], v[60:61], v[144:145]
	v_pk_mul_f32 v[56:57], v[56:57], v[148:149]
	v_pk_mul_f32 v[52:53], v[52:53], v[152:153]
	v_pk_mul_f32 v[62:63], v[62:63], v[146:147]
	v_pk_mul_f32 v[58:59], v[58:59], v[150:151]
	v_pk_mul_f32 v[54:55], v[54:55], v[154:155]
	v_pk_mul_f32 v[50:51], v[50:51], v[158:159]
	v_pk_mul_f32 v[48:49], v[48:49], v[156:157]
	v_pk_mul_f32 v[44:45], v[44:45], v[144:145]
	v_pk_mul_f32 v[40:41], v[40:41], v[148:149]
	v_pk_mul_f32 v[36:37], v[36:37], v[152:153]
	v_pk_mul_f32 v[46:47], v[46:47], v[146:147]
	v_pk_mul_f32 v[42:43], v[42:43], v[150:151]
	v_pk_mul_f32 v[38:39], v[38:39], v[154:155]
	v_pk_mul_f32 v[34:35], v[34:35], v[158:159]
	v_pk_mul_f32 v[32:33], v[32:33], v[156:157]
	v_pk_mul_f32 v[28:29], v[28:29], v[144:145]
	v_pk_mul_f32 v[24:25], v[24:25], v[148:149]
	v_pk_mul_f32 v[20:21], v[20:21], v[152:153]
	v_pk_mul_f32 v[30:31], v[30:31], v[146:147]
	v_pk_mul_f32 v[26:27], v[26:27], v[150:151]
	v_pk_mul_f32 v[22:23], v[22:23], v[154:155]
	v_pk_mul_f32 v[18:19], v[18:19], v[158:159]
	v_pk_mul_f32 v[16:17], v[16:17], v[156:157]
.LBB0_1116:
	v_cndmask_b32_e64 v166, v161, v205, s[4:5]
	v_mul_f32_e32 v144, 0xbe0293ee, v166
	v_mov_b32_e32 v145, v144
	v_fmamk_f32 v80, v80, 0x3e0293ee, v144
	v_fmamk_f32 v81, v81, 0x3e0293ee, v144
	v_fmamk_f32 v82, v82, 0x3e0293ee, v144
	v_fmamk_f32 v83, v83, 0x3e0293ee, v144
	v_fmamk_f32 v84, v84, 0x3e0293ee, v144
	v_fmamk_f32 v85, v85, 0x3e0293ee, v144
	v_fmamk_f32 v86, v86, 0x3e0293ee, v144
	v_fmamk_f32 v87, v87, 0x3e0293ee, v144
	v_fmamk_f32 v88, v88, 0x3e0293ee, v144
	v_fmamk_f32 v89, v89, 0x3e0293ee, v144
	v_fmamk_f32 v90, v90, 0x3e0293ee, v144
	v_fmamk_f32 v91, v91, 0x3e0293ee, v144
	v_fmamk_f32 v92, v92, 0x3e0293ee, v144
	v_fmamk_f32 v93, v93, 0x3e0293ee, v144
	v_fmamk_f32 v94, v94, 0x3e0293ee, v144
	v_fmac_f32_e32 v145, 0x3e0293ee, v95
	v_exp_f32_e32 v161, v80
	v_exp_f32_e32 v162, v81
	v_exp_f32_e32 v163, v82
	v_exp_f32_e32 v205, v83
	v_exp_f32_e32 v209, v84
	v_exp_f32_e32 v210, v85
	v_exp_f32_e32 v175, v86
	v_exp_f32_e32 v208, v87
	v_exp_f32_e32 v167, v88
	v_exp_f32_e32 v169, v89
	v_exp_f32_e32 v171, v90
	v_exp_f32_e32 v173, v91
	v_exp_f32_e32 v168, v92
	v_exp_f32_e32 v170, v93
	v_exp_f32_e32 v172, v94
	v_exp_f32_e32 v174, v145
	v_pk_fma_f32 v[158:159], v[64:65], s[52:53], v[144:145] op_sel_hi:[1,0,0]
	v_add_f32_e32 v64, v202, v203
	v_fmac_f32_e32 v64, v201, v186
	v_add_f32_e32 v186, v206, v207
	v_pk_fma_f32 v[156:157], v[66:67], s[52:53], v[144:145] op_sel_hi:[1,0,0]
	v_pk_fma_f32 v[152:153], v[68:69], s[52:53], v[144:145] op_sel_hi:[1,0,0]
	v_pk_fma_f32 v[148:149], v[70:71], s[52:53], v[144:145] op_sel_hi:[1,0,0]
	v_pk_fma_f32 v[146:147], v[72:73], s[52:53], v[144:145] op_sel_hi:[1,0,0]
	v_pk_fma_f32 v[154:155], v[74:75], s[52:53], v[144:145] op_sel_hi:[1,0,0]
	v_pk_fma_f32 v[150:151], v[76:77], s[52:53], v[144:145] op_sel_hi:[1,0,0]
	v_pk_fma_f32 v[144:145], v[78:79], s[52:53], v[144:145] op_sel_hi:[1,0,0]
	v_fmac_f32_e32 v186, v64, v204
	v_lshl_add_u64 v[180:181], v[180:181], 0, s[0:1]
	s_and_b64 vcc, exec, s[8:9]
	v_mov_b32_e32 v251, v187
	v_mov_b32_e32 v187, v188
	v_mov_b32_e32 v188, v248
	v_mov_b32_e32 v248, v251
	s_waitcnt lgkmcnt(0)
	s_barrier
	s_cbranch_vccnz .LBB0_1118
	v_mov_b32_e32 v201, v160
	s_branch .LBB0_1106
